# attention-out context K-slice f32 partial stores also merged with v_permlane32_swap into 64-byte row pieces
# baseline (speedup 1.0000x reference)
.LBB0_1117:
	s_add_i32 s41, s22, 2
	s_add_u32 s20, s14, 0x100
	s_addc_u32 s21, s15, 0
	s_add_i32 s42, 0, 0x10000
	s_waitcnt vmcnt(0)
	v_add_u32_e32 v102, s42, v230
	ds_read_b128 v[78:81], v102
	ds_read_b128 v[86:89], v102 offset:1024
	ds_read_b128 v[94:97], v102 offset:2048
	ds_read_b128 v[102:105], v102 offset:3072
	s_cmp_eq_u32 s38, s22
	s_cselect_b32 s22, s18, s39
	s_cselect_b32 s25, s17, s21
	s_cselect_b32 s24, s16, s20
	s_cselect_b32 s23, s19, s40
	v_lshl_add_u64 v[178:179], s[14:15], 0, v[200:201]
	s_add_i32 m0, s28, 0xc000
	ds_read_b128 v[122:125], v232
	ds_read_b128 v[126:129], v232 offset:1024
	ds_read_b128 v[130:133], v232 offset:2048
	ds_read_b128 v[134:137], v232 offset:3072
	ds_read_b128 v[154:157], v232 offset:4096
	ds_read_b128 v[158:161], v232 offset:5120
	ds_read_b128 v[170:173], v232 offset:6144
	ds_read_b128 v[174:177], v232 offset:7168
	global_load_lds_dwordx4 v[178:179], off
	v_lshl_add_u64 v[178:179], s[14:15], 0, v[202:203]
	s_add_i32 m0, s28, 0xe000
	s_nop 0
	global_load_lds_dwordx4 v[178:179], off
	s_waitcnt lgkmcnt(8)
	s_barrier
	s_waitcnt lgkmcnt(0)
	s_setprio 1
	s_waitcnt lgkmcnt(0)
	v_mfma_f32_16x16x32_f16 v[166:169], v[78:81], v[122:125], v[166:169]
	v_mfma_f32_16x16x32_f16 v[162:165], v[94:97], v[122:125], v[162:165]
	v_mfma_f32_16x16x32_f16 v[150:153], v[78:81], v[130:133], v[150:153]
	v_mfma_f32_16x16x32_f16 v[142:145], v[94:97], v[130:133], v[142:145]
	v_mfma_f32_16x16x32_f16 v[110:113], v[78:81], v[154:157], v[110:113]
	v_mfma_f32_16x16x32_f16 v[106:109], v[94:97], v[154:157], v[106:109]
	v_mfma_f32_16x16x32_f16 v[82:85], v[78:81], v[170:173], v[82:85]
	v_mfma_f32_16x16x32_f16 v[74:77], v[94:97], v[170:173], v[74:77]
	v_mfma_f32_16x16x32_f16 v[166:169], v[86:89], v[126:129], v[166:169]
	v_mfma_f32_16x16x32_f16 v[162:165], v[102:105], v[126:129], v[162:165]
	v_mfma_f32_16x16x32_f16 v[150:153], v[86:89], v[134:137], v[150:153]
	v_mfma_f32_16x16x32_f16 v[142:145], v[102:105], v[134:137], v[142:145]
	v_mfma_f32_16x16x32_f16 v[110:113], v[86:89], v[158:161], v[110:113]
	v_mfma_f32_16x16x32_f16 v[106:109], v[102:105], v[158:161], v[106:109]
	v_mfma_f32_16x16x32_f16 v[82:85], v[86:89], v[174:177], v[82:85]
	v_mfma_f32_16x16x32_f16 v[74:77], v[102:105], v[174:177], v[74:77]
	s_setprio 0
	s_barrier
	s_add_i32 s43, 0, 0x14000
	s_add_i32 s14, s42, s13
	v_add_u32_e32 v190, s43, v230
	v_lshl_add_u64 v[204:205], s[22:23], 0, v[32:33]
	s_mov_b32 m0, s14
	ds_read_b128 v[178:181], v190
	ds_read_b128 v[182:185], v190 offset:1024
	ds_read_b128 v[186:189], v190 offset:2048
	ds_read_b128 v[190:193], v190 offset:3072
	global_load_lds_dwordx4 v[204:205], off
	v_lshl_add_u64 v[206:207], s[22:23], 0, v[198:199]
	s_add_i32 m0, s14, 0x2000
	s_nop 0
	global_load_lds_dwordx4 v[206:207], off
	s_barrier
	s_waitcnt lgkmcnt(0)
	s_setprio 1
	s_waitcnt lgkmcnt(0)
	v_mfma_f32_16x16x32_f16 v[146:149], v[178:181], v[122:125], v[146:149]
	v_mfma_f32_16x16x32_f16 v[118:121], v[178:181], v[130:133], v[118:121]
	v_mfma_f32_16x16x32_f16 v[114:117], v[186:189], v[130:133], v[114:117]
	v_mfma_f32_16x16x32_f16 v[98:101], v[178:181], v[154:157], v[98:101]
	v_mfma_f32_16x16x32_f16 v[90:93], v[186:189], v[154:157], v[90:93]
	v_mfma_f32_16x16x32_f16 v[70:73], v[178:181], v[170:173], v[70:73]
	v_mfma_f32_16x16x32_f16 v[66:69], v[186:189], v[170:173], v[66:69]
	v_mfma_f32_16x16x32_f16 v[146:149], v[182:185], v[126:129], v[146:149]
	v_mfma_f32_16x16x32_f16 v[122:125], v[186:189], v[122:125], v[138:141]
	v_mfma_f32_16x16x32_f16 v[118:121], v[182:185], v[134:137], v[118:121]
	v_mfma_f32_16x16x32_f16 v[114:117], v[190:193], v[134:137], v[114:117]
	v_mfma_f32_16x16x32_f16 v[98:101], v[182:185], v[158:161], v[98:101]
	v_mfma_f32_16x16x32_f16 v[90:93], v[190:193], v[158:161], v[90:93]
	v_mfma_f32_16x16x32_f16 v[70:73], v[182:185], v[174:177], v[70:73]
	v_mfma_f32_16x16x32_f16 v[66:69], v[190:193], v[174:177], v[66:69]
	v_mfma_f32_16x16x32_f16 v[122:125], v[190:193], v[126:129], v[122:125]
	s_setprio 0
	s_mov_b32 m0, s28
	v_lshl_add_u64 v[208:209], s[24:25], 0, v[32:33]
	s_barrier
	ds_read_b128 v[126:129], v232 offset:16384
	ds_read_b128 v[130:133], v232 offset:17408
	ds_read_b128 v[134:137], v232 offset:18432
	ds_read_b128 v[138:141], v232 offset:19456
	ds_read_b128 v[154:157], v232 offset:20480
	ds_read_b128 v[158:161], v232 offset:21504
	ds_read_b128 v[170:173], v232 offset:22528
	ds_read_b128 v[174:177], v232 offset:23552
	global_load_lds_dwordx4 v[208:209], off
	v_lshl_add_u64 v[210:211], s[24:25], 0, v[198:199]
	s_mov_b32 m0, s29
	s_nop 0
	global_load_lds_dwordx4 v[210:211], off
	s_barrier
	s_waitcnt lgkmcnt(0)
	s_setprio 1
	s_waitcnt lgkmcnt(0)
	v_mfma_f32_16x16x32_f16 v[62:65], v[78:81], v[126:129], v[62:65]
	v_mfma_f32_16x16x32_f16 v[58:61], v[94:97], v[126:129], v[58:61]
	v_mfma_f32_16x16x32_f16 v[46:49], v[78:81], v[134:137], v[46:49]
	v_mfma_f32_16x16x32_f16 v[42:45], v[94:97], v[134:137], v[42:45]
	v_mfma_f32_16x16x32_f16 v[28:31], v[78:81], v[154:157], v[28:31]
	v_mfma_f32_16x16x32_f16 v[24:27], v[94:97], v[154:157], v[24:27]
	v_mfma_f32_16x16x32_f16 v[12:15], v[78:81], v[170:173], v[12:15]
	v_mfma_f32_16x16x32_f16 v[8:11], v[94:97], v[170:173], v[8:11]
	v_mfma_f32_16x16x32_f16 v[62:65], v[86:89], v[130:133], v[62:65]
	v_mfma_f32_16x16x32_f16 v[58:61], v[102:105], v[130:133], v[58:61]
	v_mfma_f32_16x16x32_f16 v[46:49], v[86:89], v[138:141], v[46:49]
	v_mfma_f32_16x16x32_f16 v[42:45], v[102:105], v[138:141], v[42:45]
	v_mfma_f32_16x16x32_f16 v[28:31], v[86:89], v[158:161], v[28:31]
	v_mfma_f32_16x16x32_f16 v[24:27], v[102:105], v[158:161], v[24:27]
	v_mfma_f32_16x16x32_f16 v[12:15], v[86:89], v[174:177], v[12:15]
	v_mfma_f32_16x16x32_f16 v[8:11], v[102:105], v[174:177], v[8:11]
	s_setprio 0
	s_barrier
	s_add_u32 s14, s22, 0x40000
	s_addc_u32 s15, s23, 0
	s_add_i32 s42, s43, s13
	v_lshl_add_u64 v[78:79], s[14:15], 0, v[32:33]
	s_mov_b32 m0, s42
	s_nop 0
	global_load_lds_dwordx4 v[78:79], off
	v_lshl_add_u64 v[78:79], s[14:15], 0, v[198:199]
	s_add_i32 m0, s42, 0x2000
	s_nop 0
	global_load_lds_dwordx4 v[78:79], off
	s_waitcnt vmcnt(6)
	s_barrier
	s_setprio 1
	v_mfma_f32_16x16x32_f16 v[54:57], v[178:181], v[126:129], v[54:57]
	v_mfma_f32_16x16x32_f16 v[50:53], v[186:189], v[126:129], v[50:53]
	v_mfma_f32_16x16x32_f16 v[38:41], v[178:181], v[134:137], v[38:41]
	v_mfma_f32_16x16x32_f16 v[34:37], v[186:189], v[134:137], v[34:37]
	v_mfma_f32_16x16x32_f16 v[20:23], v[178:181], v[154:157], v[20:23]
	v_mfma_f32_16x16x32_f16 v[16:19], v[186:189], v[154:157], v[16:19]
	v_mfma_f32_16x16x32_f16 v[4:7], v[178:181], v[170:173], v[4:7]
	v_mfma_f32_16x16x32_f16 v[0:3], v[186:189], v[170:173], v[0:3]
	v_mfma_f32_16x16x32_f16 v[54:57], v[182:185], v[130:133], v[54:57]
	v_mfma_f32_16x16x32_f16 v[50:53], v[190:193], v[130:133], v[50:53]
	v_mfma_f32_16x16x32_f16 v[38:41], v[182:185], v[138:141], v[38:41]
	v_mfma_f32_16x16x32_f16 v[34:37], v[190:193], v[138:141], v[34:37]
	v_mfma_f32_16x16x32_f16 v[20:23], v[182:185], v[158:161], v[20:23]
	v_mfma_f32_16x16x32_f16 v[16:19], v[190:193], v[158:161], v[16:19]
	v_mfma_f32_16x16x32_f16 v[4:7], v[182:185], v[174:177], v[4:7]
	v_mfma_f32_16x16x32_f16 v[0:3], v[190:193], v[174:177], v[0:3]
	s_setprio 0
	s_add_i32 s42, 0, 0x18000
	v_add_u32_e32 v102, s42, v230
	s_barrier
	ds_read_b128 v[78:81], v102
	ds_read_b128 v[86:89], v102 offset:1024
	ds_read_b128 v[94:97], v102 offset:2048
	ds_read_b128 v[102:105], v102 offset:3072
	s_add_u32 s14, s24, 0x40000
	s_addc_u32 s15, s25, 0
	s_mov_b32 m0, s30
	v_lshl_add_u64 v[138:139], s[14:15], 0, v[32:33]
	ds_read_b128 v[126:129], v232 offset:32768
	ds_read_b128 v[130:133], v232 offset:33792
	ds_read_b128 v[134:137], v232 offset:34816
	ds_read_b128 v[154:157], v232 offset:35840
	ds_read_b128 v[158:161], v232 offset:36864
	ds_read_b128 v[170:173], v232 offset:37888
	ds_read_b128 v[174:177], v232 offset:38912
	ds_read_b128 v[178:181], v232 offset:39936
	global_load_lds_dwordx4 v[138:139], off
	v_lshl_add_u64 v[138:139], s[14:15], 0, v[198:199]
	s_mov_b32 m0, s31
	s_nop 0
	global_load_lds_dwordx4 v[138:139], off
	s_waitcnt lgkmcnt(8)
	s_barrier
	s_waitcnt lgkmcnt(0)
	s_setprio 1
	s_waitcnt lgkmcnt(0)
	v_mfma_f32_16x16x32_f16 v[138:141], v[78:81], v[126:129], v[166:169]
	v_mfma_f32_16x16x32_f16 v[166:169], v[86:89], v[130:133], v[138:141]
	v_mfma_f32_16x16x32_f16 v[138:141], v[94:97], v[126:129], v[162:165]
	v_mfma_f32_16x16x32_f16 v[162:165], v[102:105], v[130:133], v[138:141]
	v_mfma_f32_16x16x32_f16 v[138:141], v[78:81], v[134:137], v[150:153]
	v_mfma_f32_16x16x32_f16 v[150:153], v[86:89], v[154:157], v[138:141]
	v_mfma_f32_16x16x32_f16 v[138:141], v[94:97], v[134:137], v[142:145]
	v_mfma_f32_16x16x32_f16 v[110:113], v[78:81], v[158:161], v[110:113]
	v_mfma_f32_16x16x32_f16 v[106:109], v[94:97], v[158:161], v[106:109]
	v_mfma_f32_16x16x32_f16 v[82:85], v[78:81], v[174:177], v[82:85]
	v_mfma_f32_16x16x32_f16 v[74:77], v[94:97], v[174:177], v[74:77]
	v_mfma_f32_16x16x32_f16 v[142:145], v[102:105], v[154:157], v[138:141]
	v_mfma_f32_16x16x32_f16 v[110:113], v[86:89], v[170:173], v[110:113]
	v_mfma_f32_16x16x32_f16 v[106:109], v[102:105], v[170:173], v[106:109]
	v_mfma_f32_16x16x32_f16 v[82:85], v[86:89], v[178:181], v[82:85]
	v_mfma_f32_16x16x32_f16 v[74:77], v[102:105], v[178:181], v[74:77]
	s_setprio 0
	s_barrier
	s_add_i32 s24, 0, 0x1c000
	v_add_u32_e32 v138, s24, v230
	s_add_i32 s14, s42, s13
	ds_read_b128 v[182:185], v138
	ds_read_b128 v[186:189], v138 offset:1024
	ds_read_b128 v[190:193], v138 offset:2048
	ds_read_b128 v[194:197], v138 offset:3072
	v_lshl_add_u64 v[138:139], v[204:205], 0, s[84:85]
	s_mov_b32 m0, s14
	s_nop 0
	global_load_lds_dwordx4 v[138:139], off
	v_lshl_add_u64 v[138:139], v[206:207], 0, s[84:85]
	s_add_i32 m0, s14, 0x2000
	s_nop 0
	global_load_lds_dwordx4 v[138:139], off
	s_barrier
	s_waitcnt lgkmcnt(0)
	s_setprio 1
	s_waitcnt lgkmcnt(0)
	v_mfma_f32_16x16x32_f16 v[138:141], v[182:185], v[126:129], v[146:149]
	v_mfma_f32_16x16x32_f16 v[122:125], v[190:193], v[126:129], v[122:125]
	v_mfma_f32_16x16x32_f16 v[118:121], v[182:185], v[134:137], v[118:121]
	v_mfma_f32_16x16x32_f16 v[114:117], v[190:193], v[134:137], v[114:117]
	v_mfma_f32_16x16x32_f16 v[98:101], v[182:185], v[158:161], v[98:101]
	v_mfma_f32_16x16x32_f16 v[90:93], v[190:193], v[158:161], v[90:93]
	v_mfma_f32_16x16x32_f16 v[70:73], v[182:185], v[174:177], v[70:73]
	v_mfma_f32_16x16x32_f16 v[66:69], v[190:193], v[174:177], v[66:69]
	v_mfma_f32_16x16x32_f16 v[146:149], v[186:189], v[130:133], v[138:141]
	v_mfma_f32_16x16x32_f16 v[138:141], v[194:197], v[130:133], v[122:125]
	v_mfma_f32_16x16x32_f16 v[118:121], v[186:189], v[154:157], v[118:121]
	v_mfma_f32_16x16x32_f16 v[114:117], v[194:197], v[154:157], v[114:117]
	v_mfma_f32_16x16x32_f16 v[98:101], v[186:189], v[170:173], v[98:101]
	v_mfma_f32_16x16x32_f16 v[90:93], v[194:197], v[170:173], v[90:93]
	v_mfma_f32_16x16x32_f16 v[70:73], v[186:189], v[178:181], v[70:73]
	v_mfma_f32_16x16x32_f16 v[66:69], v[194:197], v[178:181], v[66:69]
	s_setprio 0
	s_mov_b32 m0, s34
	v_lshl_add_u64 v[178:179], v[208:209], 0, s[84:85]
	s_barrier
	ds_read_b128 v[122:125], v232 offset:49152
	ds_read_b128 v[126:129], v232 offset:50176
	ds_read_b128 v[130:133], v232 offset:51200
	ds_read_b128 v[134:137], v232 offset:52224
	ds_read_b128 v[154:157], v232 offset:53248
	ds_read_b128 v[158:161], v232 offset:54272
	ds_read_b128 v[170:173], v232 offset:55296
	ds_read_b128 v[174:177], v232 offset:56320
	global_load_lds_dwordx4 v[178:179], off
	v_lshl_add_u64 v[178:179], v[210:211], 0, s[84:85]
	s_mov_b32 m0, s35
	s_nop 0
	global_load_lds_dwordx4 v[178:179], off
	s_barrier
	s_waitcnt lgkmcnt(0)
	s_setprio 1
	s_waitcnt lgkmcnt(0)
	v_mfma_f32_16x16x32_f16 v[62:65], v[78:81], v[122:125], v[62:65]
	v_mfma_f32_16x16x32_f16 v[58:61], v[94:97], v[122:125], v[58:61]
	v_mfma_f32_16x16x32_f16 v[46:49], v[78:81], v[130:133], v[46:49]
	v_mfma_f32_16x16x32_f16 v[42:45], v[94:97], v[130:133], v[42:45]
	v_mfma_f32_16x16x32_f16 v[28:31], v[78:81], v[154:157], v[28:31]
	v_mfma_f32_16x16x32_f16 v[24:27], v[94:97], v[154:157], v[24:27]
	v_mfma_f32_16x16x32_f16 v[12:15], v[78:81], v[170:173], v[12:15]
	v_mfma_f32_16x16x32_f16 v[8:11], v[94:97], v[170:173], v[8:11]
	v_mfma_f32_16x16x32_f16 v[62:65], v[86:89], v[126:129], v[62:65]
	v_mfma_f32_16x16x32_f16 v[58:61], v[102:105], v[126:129], v[58:61]
	v_mfma_f32_16x16x32_f16 v[46:49], v[86:89], v[134:137], v[46:49]
	v_mfma_f32_16x16x32_f16 v[42:45], v[102:105], v[134:137], v[42:45]
	v_mfma_f32_16x16x32_f16 v[28:31], v[86:89], v[158:161], v[28:31]
	v_mfma_f32_16x16x32_f16 v[24:27], v[102:105], v[158:161], v[24:27]
	v_mfma_f32_16x16x32_f16 v[12:15], v[86:89], v[174:177], v[12:15]
	v_mfma_f32_16x16x32_f16 v[8:11], v[102:105], v[174:177], v[8:11]
	s_setprio 0
	s_barrier
	s_add_u32 s14, s22, 0x40080
	s_addc_u32 s15, s23, 0
	s_add_i32 s22, s24, s13
	v_lshl_add_u64 v[78:79], s[14:15], 0, v[32:33]
	s_mov_b32 m0, s22
	s_nop 0
	global_load_lds_dwordx4 v[78:79], off
	v_lshl_add_u64 v[78:79], s[14:15], 0, v[198:199]
	s_add_i32 m0, s22, 0x2000
	s_nop 0
	global_load_lds_dwordx4 v[78:79], off
	s_waitcnt vmcnt(6)
	s_barrier
	s_setprio 1
	v_mfma_f32_16x16x32_f16 v[54:57], v[182:185], v[122:125], v[54:57]
	v_mfma_f32_16x16x32_f16 v[50:53], v[190:193], v[122:125], v[50:53]
	v_mfma_f32_16x16x32_f16 v[38:41], v[182:185], v[130:133], v[38:41]
	v_mfma_f32_16x16x32_f16 v[34:37], v[190:193], v[130:133], v[34:37]
	v_mfma_f32_16x16x32_f16 v[20:23], v[182:185], v[154:157], v[20:23]
	v_mfma_f32_16x16x32_f16 v[16:19], v[190:193], v[154:157], v[16:19]
	v_mfma_f32_16x16x32_f16 v[4:7], v[182:185], v[170:173], v[4:7]
	v_mfma_f32_16x16x32_f16 v[0:3], v[190:193], v[170:173], v[0:3]
	v_mfma_f32_16x16x32_f16 v[54:57], v[186:189], v[126:129], v[54:57]
	v_mfma_f32_16x16x32_f16 v[50:53], v[194:197], v[126:129], v[50:53]
	v_mfma_f32_16x16x32_f16 v[38:41], v[186:189], v[134:137], v[38:41]
	v_mfma_f32_16x16x32_f16 v[34:37], v[194:197], v[134:137], v[34:37]
	v_mfma_f32_16x16x32_f16 v[20:23], v[186:189], v[158:161], v[20:23]
	v_mfma_f32_16x16x32_f16 v[16:19], v[194:197], v[158:161], v[16:19]
	v_mfma_f32_16x16x32_f16 v[4:7], v[186:189], v[174:177], v[4:7]
	v_mfma_f32_16x16x32_f16 v[0:3], v[194:197], v[174:177], v[0:3]
	s_setprio 0
	s_add_u32 s39, s39, 0x100
	s_addc_u32 s40, s40, 0
	s_cmp_ge_u32 s41, s37
	s_mov_b64 s[14:15], s[20:21]
	s_mov_b32 s22, s41
	s_barrier
	s_cbranch_scc0 .LBB0_1117
	v_lshl_or_b32 v124, s12, 8, v231
	s_cmp_eq_u32 s10, 0
	s_movk_i32 s12, 0x5000
	s_cselect_b32 s12, 0xe000, s12
	v_readlane_b32 s14, v252, 51
	s_add_u32 s14, s14, s12
	v_readlane_b32 s12, v252, 52
	s_addc_u32 s15, s12, 0
	v_ashrrev_i32_e32 v125, 31, v124
	v_lshl_add_u64 v[86:87], v[124:125], 2, s[14:15]
	global_load_dwordx4 v[94:97], v[86:87], off offset:16
	global_load_dwordx4 v[102:105], v[86:87], off
	global_load_dwordx4 v[78:81], v[86:87], off offset:528
	s_nop 0
	global_load_dwordx4 v[86:89], v[86:87], off offset:512
	v_lshl_add_u32 v130, s10, 8, v229
	v_or_b32_e32 v128, 16, v130
	v_or_b32_e32 v126, 32, v130
	v_or_b32_e32 v122, 48, v130
	s_cmp_eq_u32 s11, 0
	v_ashrrev_i32_e32 v131, 31, v130
	v_ashrrev_i32_e32 v129, 31, v128
	v_ashrrev_i32_e32 v127, 31, v126
	v_ashrrev_i32_e32 v123, 31, v122
	s_cbranch_scc1 .LBB0_1120
	s_add_i32 s96, s11, -1
	s_lshl_b64 s[10:11], s[96:97], 20
	v_readlane_b32 s14, v252, 11
	v_readlane_b32 s15, v252, 12
	s_add_u32 s10, s14, s10
	s_addc_u32 s11, s15, s11
	v_lshlrev_b64 v[132:133], 2, v[124:125]
	v_lshrrev_b32_e32 v134, 5, v220
	v_mul_u32_u24_e32 v134, 48, v134
	s_nop 0
	v_sub_co_u32_e32 v132, vcc, v132, v134
	s_nop 1
	v_subbrev_co_u32_e32 v133, vcc, 0, v133, vcc
	v_lshl_add_u64 v[132:133], s[10:11], 0, v[132:133]
	s_mov_b64 s[10:11], 0x80000
	v_lshlrev_b64 v[204:205], 12, v[130:131]
	v_lshl_add_u64 v[204:205], v[204:205], 0, v[132:133]
	v_lshl_add_u64 v[212:213], v[204:205], 0, s[10:11]
	v_lshlrev_b64 v[206:207], 12, v[128:129]
	v_lshl_add_u64 v[206:207], v[206:207], 0, v[132:133]
	v_lshl_add_u64 v[214:215], v[206:207], 0, s[10:11]
	v_lshlrev_b64 v[208:209], 12, v[126:127]
	v_lshl_add_u64 v[208:209], v[208:209], 0, v[132:133]
	v_lshl_add_u64 v[216:217], v[208:209], 0, s[10:11]
	v_lshlrev_b64 v[210:211], 12, v[122:123]
	v_lshl_add_u64 v[210:211], v[210:211], 0, v[132:133]
	v_lshl_add_u64 v[218:219], v[210:211], 0, s[10:11]
	s_waitcnt vmcnt(0)
	v_pk_mul_f32 v[172:173], v[166:167], v[102:103]
	v_pk_mul_f32 v[174:175], v[168:169], v[104:105]
	v_pk_mul_f32 v[176:177], v[162:163], v[94:95]
	v_pk_mul_f32 v[178:179], v[164:165], v[96:97]
	s_nop 1
	v_permlane32_swap_b32_e32 v172, v176
	v_permlane32_swap_b32_e32 v173, v177
	v_permlane32_swap_b32_e32 v174, v178
	v_permlane32_swap_b32_e32 v175, v179
	s_nop 0
	global_store_dwordx4 v[204:205], v[172:175], off
	global_store_dwordx4 v[204:205], v[176:179], off offset:64
	v_pk_mul_f32 v[180:181], v[146:147], v[86:87]
	v_pk_mul_f32 v[182:183], v[148:149], v[88:89]
	v_pk_mul_f32 v[184:185], v[138:139], v[78:79]
	v_pk_mul_f32 v[186:187], v[140:141], v[80:81]
	s_nop 1
	v_permlane32_swap_b32_e32 v180, v184
	v_permlane32_swap_b32_e32 v181, v185
	v_permlane32_swap_b32_e32 v182, v186
	v_permlane32_swap_b32_e32 v183, v187
	s_nop 0
	global_store_dwordx4 v[204:205], v[180:183], off offset:512
	global_store_dwordx4 v[204:205], v[184:187], off offset:576
	v_pk_mul_f32 v[188:189], v[150:151], v[102:103]
	v_pk_mul_f32 v[190:191], v[152:153], v[104:105]
	v_pk_mul_f32 v[192:193], v[142:143], v[94:95]
	v_pk_mul_f32 v[194:195], v[144:145], v[96:97]
	s_nop 1
	v_permlane32_swap_b32_e32 v188, v192
	v_permlane32_swap_b32_e32 v189, v193
	v_permlane32_swap_b32_e32 v190, v194
	v_permlane32_swap_b32_e32 v191, v195
	s_nop 0
	global_store_dwordx4 v[206:207], v[188:191], off
	global_store_dwordx4 v[206:207], v[192:195], off offset:64
	v_pk_mul_f32 v[154:155], v[118:119], v[86:87]
	v_pk_mul_f32 v[156:157], v[120:121], v[88:89]
	v_pk_mul_f32 v[158:159], v[114:115], v[78:79]
	v_pk_mul_f32 v[160:161], v[116:117], v[80:81]
	s_nop 1
	v_permlane32_swap_b32_e32 v154, v158
	v_permlane32_swap_b32_e32 v155, v159
	v_permlane32_swap_b32_e32 v156, v160
	v_permlane32_swap_b32_e32 v157, v161
	s_nop 0
	global_store_dwordx4 v[206:207], v[154:157], off offset:512
	global_store_dwordx4 v[206:207], v[158:161], off offset:576
	v_pk_mul_f32 v[172:173], v[110:111], v[102:103]
	v_pk_mul_f32 v[174:175], v[112:113], v[104:105]
	v_pk_mul_f32 v[176:177], v[106:107], v[94:95]
	v_pk_mul_f32 v[178:179], v[108:109], v[96:97]
	s_nop 1
	v_permlane32_swap_b32_e32 v172, v176
	v_permlane32_swap_b32_e32 v173, v177
	v_permlane32_swap_b32_e32 v174, v178
	v_permlane32_swap_b32_e32 v175, v179
	s_nop 0
	global_store_dwordx4 v[208:209], v[172:175], off
	global_store_dwordx4 v[208:209], v[176:179], off offset:64
	v_pk_mul_f32 v[180:181], v[98:99], v[86:87]
	v_pk_mul_f32 v[182:183], v[100:101], v[88:89]
	v_pk_mul_f32 v[184:185], v[90:91], v[78:79]
	v_pk_mul_f32 v[186:187], v[92:93], v[80:81]
	s_nop 1
	v_permlane32_swap_b32_e32 v180, v184
	v_permlane32_swap_b32_e32 v181, v185
	v_permlane32_swap_b32_e32 v182, v186
	v_permlane32_swap_b32_e32 v183, v187
	s_nop 0
	global_store_dwordx4 v[208:209], v[180:183], off offset:512
	global_store_dwordx4 v[208:209], v[184:187], off offset:576
	v_pk_mul_f32 v[188:189], v[82:83], v[102:103]
	v_pk_mul_f32 v[190:191], v[84:85], v[104:105]
	v_pk_mul_f32 v[192:193], v[74:75], v[94:95]
	v_pk_mul_f32 v[194:195], v[76:77], v[96:97]
	s_nop 1
	v_permlane32_swap_b32_e32 v188, v192
	v_permlane32_swap_b32_e32 v189, v193
	v_permlane32_swap_b32_e32 v190, v194
	v_permlane32_swap_b32_e32 v191, v195
	s_nop 0
	global_store_dwordx4 v[210:211], v[188:191], off
	global_store_dwordx4 v[210:211], v[192:195], off offset:64
	v_pk_mul_f32 v[154:155], v[70:71], v[86:87]
	v_pk_mul_f32 v[156:157], v[72:73], v[88:89]
	v_pk_mul_f32 v[158:159], v[66:67], v[78:79]
	v_pk_mul_f32 v[160:161], v[68:69], v[80:81]
	s_nop 1
	v_permlane32_swap_b32_e32 v154, v158
	v_permlane32_swap_b32_e32 v155, v159
	v_permlane32_swap_b32_e32 v156, v160
	v_permlane32_swap_b32_e32 v157, v161
	s_nop 0
	global_store_dwordx4 v[210:211], v[154:157], off offset:512
	global_store_dwordx4 v[210:211], v[158:161], off offset:576
	v_pk_mul_f32 v[172:173], v[62:63], v[102:103]
	v_pk_mul_f32 v[174:175], v[64:65], v[104:105]
	v_pk_mul_f32 v[176:177], v[58:59], v[94:95]
	v_pk_mul_f32 v[178:179], v[60:61], v[96:97]
	s_nop 1
	v_permlane32_swap_b32_e32 v172, v176
	v_permlane32_swap_b32_e32 v173, v177
	v_permlane32_swap_b32_e32 v174, v178
	v_permlane32_swap_b32_e32 v175, v179
	s_nop 0
	global_store_dwordx4 v[212:213], v[172:175], off
	global_store_dwordx4 v[212:213], v[176:179], off offset:64
	v_pk_mul_f32 v[180:181], v[54:55], v[86:87]
	v_pk_mul_f32 v[182:183], v[56:57], v[88:89]
	v_pk_mul_f32 v[184:185], v[50:51], v[78:79]
	v_pk_mul_f32 v[186:187], v[52:53], v[80:81]
	s_nop 1
	v_permlane32_swap_b32_e32 v180, v184
	v_permlane32_swap_b32_e32 v181, v185
	v_permlane32_swap_b32_e32 v182, v186
	v_permlane32_swap_b32_e32 v183, v187
	s_nop 0
	global_store_dwordx4 v[212:213], v[180:183], off offset:512
	global_store_dwordx4 v[212:213], v[184:187], off offset:576
	v_pk_mul_f32 v[188:189], v[46:47], v[102:103]
	v_pk_mul_f32 v[190:191], v[48:49], v[104:105]
	v_pk_mul_f32 v[192:193], v[42:43], v[94:95]
	v_pk_mul_f32 v[194:195], v[44:45], v[96:97]
	s_nop 1
	v_permlane32_swap_b32_e32 v188, v192
	v_permlane32_swap_b32_e32 v189, v193
	v_permlane32_swap_b32_e32 v190, v194
	v_permlane32_swap_b32_e32 v191, v195
	s_nop 0
	global_store_dwordx4 v[214:215], v[188:191], off
	global_store_dwordx4 v[214:215], v[192:195], off offset:64
	v_pk_mul_f32 v[154:155], v[38:39], v[86:87]
	v_pk_mul_f32 v[156:157], v[40:41], v[88:89]
	v_pk_mul_f32 v[158:159], v[34:35], v[78:79]
	v_pk_mul_f32 v[160:161], v[36:37], v[80:81]
	s_nop 1
	v_permlane32_swap_b32_e32 v154, v158
	v_permlane32_swap_b32_e32 v155, v159
	v_permlane32_swap_b32_e32 v156, v160
	v_permlane32_swap_b32_e32 v157, v161
	s_nop 0
	global_store_dwordx4 v[214:215], v[154:157], off offset:512
	global_store_dwordx4 v[214:215], v[158:161], off offset:576
	v_pk_mul_f32 v[172:173], v[28:29], v[102:103]
	v_pk_mul_f32 v[174:175], v[30:31], v[104:105]
	v_pk_mul_f32 v[176:177], v[24:25], v[94:95]
	v_pk_mul_f32 v[178:179], v[26:27], v[96:97]
	s_nop 1
	v_permlane32_swap_b32_e32 v172, v176
	v_permlane32_swap_b32_e32 v173, v177
	v_permlane32_swap_b32_e32 v174, v178
	v_permlane32_swap_b32_e32 v175, v179
	s_nop 0
	global_store_dwordx4 v[216:217], v[172:175], off
	global_store_dwordx4 v[216:217], v[176:179], off offset:64
	v_pk_mul_f32 v[180:181], v[20:21], v[86:87]
	v_pk_mul_f32 v[182:183], v[22:23], v[88:89]
	v_pk_mul_f32 v[184:185], v[16:17], v[78:79]
	v_pk_mul_f32 v[186:187], v[18:19], v[80:81]
	s_nop 1
	v_permlane32_swap_b32_e32 v180, v184
	v_permlane32_swap_b32_e32 v181, v185
	v_permlane32_swap_b32_e32 v182, v186
	v_permlane32_swap_b32_e32 v183, v187
	s_nop 0
	global_store_dwordx4 v[216:217], v[180:183], off offset:512
	global_store_dwordx4 v[216:217], v[184:187], off offset:576
	v_pk_mul_f32 v[188:189], v[12:13], v[102:103]
	v_pk_mul_f32 v[190:191], v[14:15], v[104:105]
	v_pk_mul_f32 v[192:193], v[8:9], v[94:95]
	v_pk_mul_f32 v[194:195], v[10:11], v[96:97]
	s_nop 1
	v_permlane32_swap_b32_e32 v188, v192
	v_permlane32_swap_b32_e32 v189, v193
	v_permlane32_swap_b32_e32 v190, v194
	v_permlane32_swap_b32_e32 v191, v195
	s_nop 0
	global_store_dwordx4 v[218:219], v[188:191], off
	global_store_dwordx4 v[218:219], v[192:195], off offset:64
	v_pk_mul_f32 v[154:155], v[4:5], v[86:87]
	v_pk_mul_f32 v[156:157], v[6:7], v[88:89]
	v_pk_mul_f32 v[158:159], v[0:1], v[78:79]
	v_pk_mul_f32 v[160:161], v[2:3], v[80:81]
	s_nop 1
	v_permlane32_swap_b32_e32 v154, v158
	v_permlane32_swap_b32_e32 v155, v159
	v_permlane32_swap_b32_e32 v156, v160
	v_permlane32_swap_b32_e32 v157, v161
	s_nop 0
	global_store_dwordx4 v[218:219], v[154:157], off offset:512
	global_store_dwordx4 v[218:219], v[158:161], off offset:576
	s_cbranch_execnz .LBB0_1104
	s_branch .LBB0_1103

.LBB0_1365:
	s_add_i32 s46, s14, 2
	s_add_u32 s12, s10, 0x100
	s_addc_u32 s13, s11, 0
	s_add_i32 s47, 0, 0x10000
	v_add_u32_e32 v134, s47, v230
	ds_read_b128 v[106:109], v134
	ds_read_b128 v[110:113], v134 offset:1024
	ds_read_b128 v[114:117], v134 offset:2048
	ds_read_b128 v[134:137], v134 offset:3072
	s_cmp_eq_u32 s43, s14
	s_cselect_b32 s14, s8, s44
	s_cselect_b32 s17, s7, s13
	s_cselect_b32 s16, s6, s12
	s_cselect_b32 s15, s9, s45
	v_lshl_add_u64 v[178:179], s[10:11], 0, v[184:185]
	s_add_i32 m0, s24, 0xc000
	ds_read_b128 v[138:141], v232
	ds_read_b128 v[150:153], v232 offset:1024
	ds_read_b128 v[154:157], v232 offset:2048
	ds_read_b128 v[158:161], v232 offset:3072
	ds_read_b128 v[162:165], v232 offset:4096
	ds_read_b128 v[166:169], v232 offset:5120
	ds_read_b128 v[170:173], v232 offset:6144
	ds_read_b128 v[174:177], v232 offset:7168
	global_load_lds_dwordx4 v[178:179], off
	v_lshl_add_u64 v[178:179], s[10:11], 0, v[186:187]
	s_add_i32 m0, s24, 0xe000
	s_nop 0
	global_load_lds_dwordx4 v[178:179], off
	s_waitcnt lgkmcnt(8)
	s_barrier
	s_waitcnt lgkmcnt(0)
	s_setprio 1
	s_waitcnt lgkmcnt(0)
	v_mfma_f32_16x16x32_f16 v[146:149], v[106:109], v[138:141], v[146:149]
	v_mfma_f32_16x16x32_f16 v[142:145], v[114:117], v[138:141], v[142:145]
	v_mfma_f32_16x16x32_f16 v[130:133], v[106:109], v[154:157], v[130:133]
	v_mfma_f32_16x16x32_f16 v[122:125], v[114:117], v[154:157], v[122:125]
	v_mfma_f32_16x16x32_f16 v[94:97], v[106:109], v[162:165], v[94:97]
	v_mfma_f32_16x16x32_f16 v[90:93], v[114:117], v[162:165], v[90:93]
	v_mfma_f32_16x16x32_f16 v[78:81], v[106:109], v[170:173], v[78:81]
	v_mfma_f32_16x16x32_f16 v[74:77], v[114:117], v[170:173], v[74:77]
	v_mfma_f32_16x16x32_f16 v[146:149], v[110:113], v[150:153], v[146:149]
	v_mfma_f32_16x16x32_f16 v[142:145], v[134:137], v[150:153], v[142:145]
	v_mfma_f32_16x16x32_f16 v[130:133], v[110:113], v[158:161], v[130:133]
	v_mfma_f32_16x16x32_f16 v[122:125], v[134:137], v[158:161], v[122:125]
	v_mfma_f32_16x16x32_f16 v[94:97], v[110:113], v[166:169], v[94:97]
	v_mfma_f32_16x16x32_f16 v[90:93], v[134:137], v[166:169], v[90:93]
	v_mfma_f32_16x16x32_f16 v[78:81], v[110:113], v[174:177], v[78:81]
	v_mfma_f32_16x16x32_f16 v[74:77], v[134:137], v[174:177], v[74:77]
	s_setprio 0
	s_barrier
	s_add_i32 s48, 0, 0x14000
	s_add_i32 s10, s47, s23
	v_add_u32_e32 v196, s48, v230
	v_lshl_add_u64 v[200:201], s[14:15], 0, v[32:33]
	s_mov_b32 m0, s10
	ds_read_b128 v[178:181], v196
	ds_read_b128 v[188:191], v196 offset:1024
	ds_read_b128 v[192:195], v196 offset:2048
	ds_read_b128 v[196:199], v196 offset:3072
	global_load_lds_dwordx4 v[200:201], off
	v_lshl_add_u64 v[202:203], s[14:15], 0, v[182:183]
	s_add_i32 m0, s10, 0x2000
	s_nop 0
	global_load_lds_dwordx4 v[202:203], off
	s_barrier
	s_waitcnt lgkmcnt(0)
	s_setprio 1
	s_waitcnt lgkmcnt(0)
	v_mfma_f32_16x16x32_f16 v[126:129], v[178:181], v[138:141], v[126:129]
	v_mfma_f32_16x16x32_f16 v[118:121], v[192:195], v[138:141], v[118:121]
	v_mfma_f32_16x16x32_f16 v[102:105], v[178:181], v[154:157], v[102:105]
	v_mfma_f32_16x16x32_f16 v[98:101], v[192:195], v[154:157], v[98:101]
	v_mfma_f32_16x16x32_f16 v[86:89], v[178:181], v[162:165], v[86:89]
	v_mfma_f32_16x16x32_f16 v[82:85], v[192:195], v[162:165], v[82:85]
	v_mfma_f32_16x16x32_f16 v[70:73], v[178:181], v[170:173], v[70:73]
	v_mfma_f32_16x16x32_f16 v[66:69], v[192:195], v[170:173], v[66:69]
	v_mfma_f32_16x16x32_f16 v[126:129], v[188:191], v[150:153], v[126:129]
	v_mfma_f32_16x16x32_f16 v[118:121], v[196:199], v[150:153], v[118:121]
	v_mfma_f32_16x16x32_f16 v[102:105], v[188:191], v[158:161], v[102:105]
	v_mfma_f32_16x16x32_f16 v[98:101], v[196:199], v[158:161], v[98:101]
	v_mfma_f32_16x16x32_f16 v[86:89], v[188:191], v[166:169], v[86:89]
	v_mfma_f32_16x16x32_f16 v[82:85], v[196:199], v[166:169], v[82:85]
	v_mfma_f32_16x16x32_f16 v[70:73], v[188:191], v[174:177], v[70:73]
	v_mfma_f32_16x16x32_f16 v[66:69], v[196:199], v[174:177], v[66:69]
	s_setprio 0
	s_mov_b32 m0, s24
	v_lshl_add_u64 v[204:205], s[16:17], 0, v[32:33]
	s_barrier
	ds_read_b128 v[138:141], v232 offset:16384
	ds_read_b128 v[150:153], v232 offset:17408
	ds_read_b128 v[154:157], v232 offset:18432
	ds_read_b128 v[158:161], v232 offset:19456
	ds_read_b128 v[162:165], v232 offset:20480
	ds_read_b128 v[166:169], v232 offset:21504
	ds_read_b128 v[170:173], v232 offset:22528
	ds_read_b128 v[174:177], v232 offset:23552
	global_load_lds_dwordx4 v[204:205], off
	v_lshl_add_u64 v[206:207], s[16:17], 0, v[182:183]
	s_mov_b32 m0, s25
	s_nop 0
	global_load_lds_dwordx4 v[206:207], off
	s_barrier
	s_waitcnt lgkmcnt(0)
	s_setprio 1
	s_waitcnt lgkmcnt(0)
	v_mfma_f32_16x16x32_f16 v[62:65], v[106:109], v[138:141], v[62:65]
	v_mfma_f32_16x16x32_f16 v[58:61], v[114:117], v[138:141], v[58:61]
	v_mfma_f32_16x16x32_f16 v[46:49], v[106:109], v[154:157], v[46:49]
	v_mfma_f32_16x16x32_f16 v[42:45], v[114:117], v[154:157], v[42:45]
	v_mfma_f32_16x16x32_f16 v[28:31], v[106:109], v[162:165], v[28:31]
	v_mfma_f32_16x16x32_f16 v[24:27], v[114:117], v[162:165], v[24:27]
	v_mfma_f32_16x16x32_f16 v[12:15], v[106:109], v[170:173], v[12:15]
	v_mfma_f32_16x16x32_f16 v[8:11], v[114:117], v[170:173], v[8:11]
	v_mfma_f32_16x16x32_f16 v[62:65], v[110:113], v[150:153], v[62:65]
	v_mfma_f32_16x16x32_f16 v[58:61], v[134:137], v[150:153], v[58:61]
	v_mfma_f32_16x16x32_f16 v[46:49], v[110:113], v[158:161], v[46:49]
	v_mfma_f32_16x16x32_f16 v[42:45], v[134:137], v[158:161], v[42:45]
	v_mfma_f32_16x16x32_f16 v[28:31], v[110:113], v[166:169], v[28:31]
	v_mfma_f32_16x16x32_f16 v[24:27], v[134:137], v[166:169], v[24:27]
	v_mfma_f32_16x16x32_f16 v[12:15], v[110:113], v[174:177], v[12:15]
	v_mfma_f32_16x16x32_f16 v[8:11], v[134:137], v[174:177], v[8:11]
	s_setprio 0
	s_barrier
	s_add_u32 s10, s14, 0xb0000
	s_addc_u32 s11, s15, 0
	s_add_i32 s47, s48, s23
	v_lshl_add_u64 v[106:107], s[10:11], 0, v[32:33]
	s_mov_b32 m0, s47
	s_nop 0
	global_load_lds_dwordx4 v[106:107], off
	v_lshl_add_u64 v[106:107], s[10:11], 0, v[182:183]
	s_add_i32 m0, s47, 0x2000
	s_nop 0
	global_load_lds_dwordx4 v[106:107], off
	s_waitcnt vmcnt(6)
	s_barrier
	s_setprio 1
	v_mfma_f32_16x16x32_f16 v[54:57], v[178:181], v[138:141], v[54:57]
	v_mfma_f32_16x16x32_f16 v[50:53], v[192:195], v[138:141], v[50:53]
	v_mfma_f32_16x16x32_f16 v[38:41], v[178:181], v[154:157], v[38:41]
	v_mfma_f32_16x16x32_f16 v[34:37], v[192:195], v[154:157], v[34:37]
	v_mfma_f32_16x16x32_f16 v[20:23], v[178:181], v[162:165], v[20:23]
	v_mfma_f32_16x16x32_f16 v[16:19], v[192:195], v[162:165], v[16:19]
	v_mfma_f32_16x16x32_f16 v[4:7], v[178:181], v[170:173], v[4:7]
	v_mfma_f32_16x16x32_f16 v[0:3], v[192:195], v[170:173], v[0:3]
	v_mfma_f32_16x16x32_f16 v[54:57], v[188:191], v[150:153], v[54:57]
	v_mfma_f32_16x16x32_f16 v[50:53], v[196:199], v[150:153], v[50:53]
	v_mfma_f32_16x16x32_f16 v[38:41], v[188:191], v[158:161], v[38:41]
	v_mfma_f32_16x16x32_f16 v[34:37], v[196:199], v[158:161], v[34:37]
	v_mfma_f32_16x16x32_f16 v[20:23], v[188:191], v[166:169], v[20:23]
	v_mfma_f32_16x16x32_f16 v[16:19], v[196:199], v[166:169], v[16:19]
	v_mfma_f32_16x16x32_f16 v[4:7], v[188:191], v[174:177], v[4:7]
	v_mfma_f32_16x16x32_f16 v[0:3], v[196:199], v[174:177], v[0:3]
	s_setprio 0
	s_add_i32 s47, 0, 0x18000
	v_add_u32_e32 v134, s47, v230
	s_barrier
	ds_read_b128 v[106:109], v134
	ds_read_b128 v[110:113], v134 offset:1024
	ds_read_b128 v[114:117], v134 offset:2048
	ds_read_b128 v[134:137], v134 offset:3072
	s_add_u32 s10, s16, 0xb0000
	s_addc_u32 s11, s17, 0
	s_mov_b32 m0, s26
	v_lshl_add_u64 v[178:179], s[10:11], 0, v[32:33]
	ds_read_b128 v[138:141], v232 offset:32768
	ds_read_b128 v[150:153], v232 offset:33792
	ds_read_b128 v[154:157], v232 offset:34816
	ds_read_b128 v[158:161], v232 offset:35840
	ds_read_b128 v[162:165], v232 offset:36864
	ds_read_b128 v[166:169], v232 offset:37888
	ds_read_b128 v[170:173], v232 offset:38912
	ds_read_b128 v[174:177], v232 offset:39936
	global_load_lds_dwordx4 v[178:179], off
	v_lshl_add_u64 v[178:179], s[10:11], 0, v[182:183]
	s_mov_b32 m0, s27
	s_nop 0
	global_load_lds_dwordx4 v[178:179], off
	s_waitcnt lgkmcnt(8)
	s_barrier
	s_waitcnt lgkmcnt(0)
	s_setprio 1
	s_waitcnt lgkmcnt(0)
	v_mfma_f32_16x16x32_f16 v[146:149], v[106:109], v[138:141], v[146:149]
	v_mfma_f32_16x16x32_f16 v[142:145], v[114:117], v[138:141], v[142:145]
	v_mfma_f32_16x16x32_f16 v[130:133], v[106:109], v[154:157], v[130:133]
	v_mfma_f32_16x16x32_f16 v[122:125], v[114:117], v[154:157], v[122:125]
	v_mfma_f32_16x16x32_f16 v[94:97], v[106:109], v[162:165], v[94:97]
	v_mfma_f32_16x16x32_f16 v[90:93], v[114:117], v[162:165], v[90:93]
	v_mfma_f32_16x16x32_f16 v[78:81], v[106:109], v[170:173], v[78:81]
	v_mfma_f32_16x16x32_f16 v[74:77], v[114:117], v[170:173], v[74:77]
	v_mfma_f32_16x16x32_f16 v[146:149], v[110:113], v[150:153], v[146:149]
	v_mfma_f32_16x16x32_f16 v[142:145], v[134:137], v[150:153], v[142:145]
	v_mfma_f32_16x16x32_f16 v[130:133], v[110:113], v[158:161], v[130:133]
	v_mfma_f32_16x16x32_f16 v[122:125], v[134:137], v[158:161], v[122:125]
	v_mfma_f32_16x16x32_f16 v[94:97], v[110:113], v[166:169], v[94:97]
	v_mfma_f32_16x16x32_f16 v[90:93], v[134:137], v[166:169], v[90:93]
	v_mfma_f32_16x16x32_f16 v[78:81], v[110:113], v[174:177], v[78:81]
	v_mfma_f32_16x16x32_f16 v[74:77], v[134:137], v[174:177], v[74:77]
	s_setprio 0
	s_barrier
	s_add_i32 s16, 0, 0x1c000
	s_add_i32 s10, s47, s23
	v_add_u32_e32 v196, s16, v230
	v_lshl_add_u64 v[200:201], v[200:201], 0, s[84:85]
	s_mov_b32 m0, s10
	ds_read_b128 v[178:181], v196
	ds_read_b128 v[188:191], v196 offset:1024
	ds_read_b128 v[192:195], v196 offset:2048
	ds_read_b128 v[196:199], v196 offset:3072
	global_load_lds_dwordx4 v[200:201], off
	v_lshl_add_u64 v[200:201], v[202:203], 0, s[84:85]
	s_add_i32 m0, s10, 0x2000
	s_nop 0
	global_load_lds_dwordx4 v[200:201], off
	s_barrier
	s_waitcnt lgkmcnt(0)
	s_setprio 1
	s_waitcnt lgkmcnt(0)
	v_mfma_f32_16x16x32_f16 v[126:129], v[178:181], v[138:141], v[126:129]
	v_mfma_f32_16x16x32_f16 v[118:121], v[192:195], v[138:141], v[118:121]
	v_mfma_f32_16x16x32_f16 v[102:105], v[178:181], v[154:157], v[102:105]
	v_mfma_f32_16x16x32_f16 v[98:101], v[192:195], v[154:157], v[98:101]
	v_mfma_f32_16x16x32_f16 v[86:89], v[178:181], v[162:165], v[86:89]
	v_mfma_f32_16x16x32_f16 v[82:85], v[192:195], v[162:165], v[82:85]
	v_mfma_f32_16x16x32_f16 v[70:73], v[178:181], v[170:173], v[70:73]
	v_mfma_f32_16x16x32_f16 v[66:69], v[192:195], v[170:173], v[66:69]
	v_mfma_f32_16x16x32_f16 v[126:129], v[188:191], v[150:153], v[126:129]
	v_mfma_f32_16x16x32_f16 v[118:121], v[196:199], v[150:153], v[118:121]
	v_mfma_f32_16x16x32_f16 v[102:105], v[188:191], v[158:161], v[102:105]
	v_mfma_f32_16x16x32_f16 v[98:101], v[196:199], v[158:161], v[98:101]
	v_mfma_f32_16x16x32_f16 v[86:89], v[188:191], v[166:169], v[86:89]
	v_mfma_f32_16x16x32_f16 v[82:85], v[196:199], v[166:169], v[82:85]
	v_mfma_f32_16x16x32_f16 v[70:73], v[188:191], v[174:177], v[70:73]
	v_mfma_f32_16x16x32_f16 v[66:69], v[196:199], v[174:177], v[66:69]
	s_setprio 0
	s_mov_b32 m0, s29
	v_lshl_add_u64 v[200:201], v[204:205], 0, s[84:85]
	s_barrier
	ds_read_b128 v[138:141], v232 offset:49152
	ds_read_b128 v[150:153], v232 offset:50176
	ds_read_b128 v[154:157], v232 offset:51200
	ds_read_b128 v[158:161], v232 offset:52224
	ds_read_b128 v[162:165], v232 offset:53248
	ds_read_b128 v[166:169], v232 offset:54272
	ds_read_b128 v[170:173], v232 offset:55296
	ds_read_b128 v[174:177], v232 offset:56320
	global_load_lds_dwordx4 v[200:201], off
	v_lshl_add_u64 v[200:201], v[206:207], 0, s[84:85]
	s_mov_b32 m0, s30
	s_nop 0
	global_load_lds_dwordx4 v[200:201], off
	s_barrier
	s_waitcnt lgkmcnt(0)
	s_setprio 1
	s_waitcnt lgkmcnt(0)
	v_mfma_f32_16x16x32_f16 v[62:65], v[106:109], v[138:141], v[62:65]
	v_mfma_f32_16x16x32_f16 v[58:61], v[114:117], v[138:141], v[58:61]
	v_mfma_f32_16x16x32_f16 v[46:49], v[106:109], v[154:157], v[46:49]
	v_mfma_f32_16x16x32_f16 v[42:45], v[114:117], v[154:157], v[42:45]
	v_mfma_f32_16x16x32_f16 v[28:31], v[106:109], v[162:165], v[28:31]
	v_mfma_f32_16x16x32_f16 v[24:27], v[114:117], v[162:165], v[24:27]
	v_mfma_f32_16x16x32_f16 v[12:15], v[106:109], v[170:173], v[12:15]
	v_mfma_f32_16x16x32_f16 v[8:11], v[114:117], v[170:173], v[8:11]
	v_mfma_f32_16x16x32_f16 v[62:65], v[110:113], v[150:153], v[62:65]
	v_mfma_f32_16x16x32_f16 v[58:61], v[134:137], v[150:153], v[58:61]
	v_mfma_f32_16x16x32_f16 v[46:49], v[110:113], v[158:161], v[46:49]
	v_mfma_f32_16x16x32_f16 v[42:45], v[134:137], v[158:161], v[42:45]
	v_mfma_f32_16x16x32_f16 v[28:31], v[110:113], v[166:169], v[28:31]
	v_mfma_f32_16x16x32_f16 v[24:27], v[134:137], v[166:169], v[24:27]
	v_mfma_f32_16x16x32_f16 v[12:15], v[110:113], v[174:177], v[12:15]
	v_mfma_f32_16x16x32_f16 v[8:11], v[134:137], v[174:177], v[8:11]
	s_setprio 0
	s_barrier
	s_add_u32 s10, s14, 0xb0080
	s_addc_u32 s11, s15, 0
	s_add_i32 s14, s16, s23
	v_lshl_add_u64 v[106:107], s[10:11], 0, v[32:33]
	s_mov_b32 m0, s14
	s_nop 0
	global_load_lds_dwordx4 v[106:107], off
	v_lshl_add_u64 v[106:107], s[10:11], 0, v[182:183]
	s_add_i32 m0, s14, 0x2000
	s_nop 0
	global_load_lds_dwordx4 v[106:107], off
	s_waitcnt vmcnt(6)
	s_barrier
	s_setprio 1
	v_mfma_f32_16x16x32_f16 v[54:57], v[178:181], v[138:141], v[54:57]
	v_mfma_f32_16x16x32_f16 v[50:53], v[192:195], v[138:141], v[50:53]
	v_mfma_f32_16x16x32_f16 v[38:41], v[178:181], v[154:157], v[38:41]
	v_mfma_f32_16x16x32_f16 v[34:37], v[192:195], v[154:157], v[34:37]
	v_mfma_f32_16x16x32_f16 v[20:23], v[178:181], v[162:165], v[20:23]
	v_mfma_f32_16x16x32_f16 v[16:19], v[192:195], v[162:165], v[16:19]
	v_mfma_f32_16x16x32_f16 v[4:7], v[178:181], v[170:173], v[4:7]
	v_mfma_f32_16x16x32_f16 v[0:3], v[192:195], v[170:173], v[0:3]
	v_mfma_f32_16x16x32_f16 v[54:57], v[188:191], v[150:153], v[54:57]
	v_mfma_f32_16x16x32_f16 v[50:53], v[196:199], v[150:153], v[50:53]
	v_mfma_f32_16x16x32_f16 v[38:41], v[188:191], v[158:161], v[38:41]
	v_mfma_f32_16x16x32_f16 v[34:37], v[196:199], v[158:161], v[34:37]
	v_mfma_f32_16x16x32_f16 v[20:23], v[188:191], v[166:169], v[20:23]
	v_mfma_f32_16x16x32_f16 v[16:19], v[196:199], v[166:169], v[16:19]
	v_mfma_f32_16x16x32_f16 v[4:7], v[188:191], v[174:177], v[4:7]
	v_mfma_f32_16x16x32_f16 v[0:3], v[196:199], v[174:177], v[0:3]
	s_setprio 0
	s_add_u32 s44, s44, 0x100
	s_addc_u32 s45, s45, 0
	s_cmp_ge_u32 s46, s42
	s_mov_b64 s[10:11], s[12:13]
	s_mov_b32 s14, s46
	s_barrier
	s_cbranch_scc0 .LBB0_1365
	s_cmp_eq_u32 s40, 0
	s_cselect_b32 s6, 0x9000, 0
	v_lshl_or_b32 v106, s41, 8, v231
	s_add_u32 s6, s31, s6
	s_addc_u32 s7, s34, 0
	v_ashrrev_i32_e32 v107, 31, v106
	v_lshl_add_u64 v[116:117], v[106:107], 2, s[6:7]
	global_load_dwordx4 v[108:111], v[116:117], off offset:16
	global_load_dwordx4 v[112:115], v[116:117], off
	s_cmp_eq_u32 s39, 0
	s_waitcnt vmcnt(0)
	v_pk_mul_f32 v[194:195], v[110:111], 0.5 op_sel_hi:[1,0]
	v_pk_mul_f32 v[198:199], v[114:115], 0.5 op_sel_hi:[1,0]
	v_pk_mul_f32 v[202:203], v[112:113], 0.5 op_sel_hi:[1,0]
	v_pk_mul_f32 v[200:201], v[108:109], 0.5 op_sel_hi:[1,0]
	global_load_dwordx4 v[108:111], v[116:117], off offset:528
	global_load_dwordx4 v[112:115], v[116:117], off offset:512
	s_waitcnt vmcnt(0)
	v_pk_mul_f32 v[188:189], v[110:111], 0.5 op_sel_hi:[1,0]
	v_pk_mul_f32 v[196:197], v[112:113], 0.5 op_sel_hi:[1,0]
	v_lshl_add_u32 v112, s40, 8, v229
	v_pk_mul_f32 v[190:191], v[114:115], 0.5 op_sel_hi:[1,0]
	v_pk_mul_f32 v[192:193], v[108:109], 0.5 op_sel_hi:[1,0]
	v_or_b32_e32 v114, 16, v112
	v_or_b32_e32 v110, 32, v112
	v_or_b32_e32 v108, 48, v112
	v_ashrrev_i32_e32 v113, 31, v112
	v_ashrrev_i32_e32 v115, 31, v114
	v_ashrrev_i32_e32 v111, 31, v110
	v_ashrrev_i32_e32 v109, 31, v108
	s_cbranch_scc1 .LBB0_1368
	s_add_i32 s96, s39, -1
	s_lshl_b64 s[6:7], s[96:97], 20
	v_readlane_b32 s8, v252, 11
	v_readlane_b32 s9, v252, 12
	s_add_u32 s6, s8, s6
	s_addc_u32 s7, s9, s7
	v_lshlrev_b64 v[138:139], 2, v[106:107]
	v_lshrrev_b32_e32 v150, 5, v220
	v_mul_u32_u24_e32 v150, 48, v150
	s_nop 0
	v_sub_co_u32_e32 v138, vcc, v138, v150
	s_nop 1
	v_subbrev_co_u32_e32 v139, vcc, 0, v139, vcc
	v_lshl_add_u64 v[138:139], s[6:7], 0, v[138:139]
	s_mov_b64 s[6:7], 0x80000
	v_lshlrev_b64 v[204:205], 12, v[112:113]
	v_lshl_add_u64 v[204:205], v[204:205], 0, v[138:139]
	v_lshl_add_u64 v[212:213], v[204:205], 0, s[6:7]
	v_lshlrev_b64 v[206:207], 12, v[114:115]
	v_lshl_add_u64 v[206:207], v[206:207], 0, v[138:139]
	v_lshl_add_u64 v[214:215], v[206:207], 0, s[6:7]
	v_lshlrev_b64 v[208:209], 12, v[110:111]
	v_lshl_add_u64 v[208:209], v[208:209], 0, v[138:139]
	v_lshl_add_u64 v[216:217], v[208:209], 0, s[6:7]
	v_lshlrev_b64 v[210:211], 12, v[108:109]
	v_lshl_add_u64 v[210:211], v[210:211], 0, v[138:139]
	v_lshl_add_u64 v[218:219], v[210:211], 0, s[6:7]
	s_waitcnt vmcnt(0)
	v_pk_mul_f32 v[152:153], v[146:147], v[202:203]
	v_pk_mul_f32 v[154:155], v[148:149], v[198:199]
	v_pk_mul_f32 v[156:157], v[142:143], v[200:201]
	v_pk_mul_f32 v[158:159], v[144:145], v[194:195]
	s_nop 1
	v_permlane32_swap_b32_e32 v152, v156
	v_permlane32_swap_b32_e32 v153, v157
	v_permlane32_swap_b32_e32 v154, v158
	v_permlane32_swap_b32_e32 v155, v159
	s_nop 0
	global_store_dwordx4 v[204:205], v[152:155], off
	global_store_dwordx4 v[204:205], v[156:159], off offset:64
	v_pk_mul_f32 v[160:161], v[126:127], v[196:197]
	v_pk_mul_f32 v[162:163], v[128:129], v[190:191]
	v_pk_mul_f32 v[164:165], v[118:119], v[192:193]
	v_pk_mul_f32 v[166:167], v[120:121], v[188:189]
	s_nop 1
	v_permlane32_swap_b32_e32 v160, v164
	v_permlane32_swap_b32_e32 v161, v165
	v_permlane32_swap_b32_e32 v162, v166
	v_permlane32_swap_b32_e32 v163, v167
	s_nop 0
	global_store_dwordx4 v[204:205], v[160:163], off offset:512
	global_store_dwordx4 v[204:205], v[164:167], off offset:576
	v_pk_mul_f32 v[168:169], v[130:131], v[202:203]
	v_pk_mul_f32 v[170:171], v[132:133], v[198:199]
	v_pk_mul_f32 v[172:173], v[122:123], v[200:201]
	v_pk_mul_f32 v[174:175], v[124:125], v[194:195]
	s_nop 1
	v_permlane32_swap_b32_e32 v168, v172
	v_permlane32_swap_b32_e32 v169, v173
	v_permlane32_swap_b32_e32 v170, v174
	v_permlane32_swap_b32_e32 v171, v175
	s_nop 0
	global_store_dwordx4 v[206:207], v[168:171], off
	global_store_dwordx4 v[206:207], v[172:175], off offset:64
	v_pk_mul_f32 v[176:177], v[102:103], v[196:197]
	v_pk_mul_f32 v[178:179], v[104:105], v[190:191]
	v_pk_mul_f32 v[180:181], v[98:99], v[192:193]
	v_pk_mul_f32 v[182:183], v[100:101], v[188:189]
	s_nop 1
	v_permlane32_swap_b32_e32 v176, v180
	v_permlane32_swap_b32_e32 v177, v181
	v_permlane32_swap_b32_e32 v178, v182
	v_permlane32_swap_b32_e32 v179, v183
	s_nop 0
	global_store_dwordx4 v[206:207], v[176:179], off offset:512
	global_store_dwordx4 v[206:207], v[180:183], off offset:576
	v_pk_mul_f32 v[152:153], v[94:95], v[202:203]
	v_pk_mul_f32 v[154:155], v[96:97], v[198:199]
	v_pk_mul_f32 v[156:157], v[90:91], v[200:201]
	v_pk_mul_f32 v[158:159], v[92:93], v[194:195]
	s_nop 1
	v_permlane32_swap_b32_e32 v152, v156
	v_permlane32_swap_b32_e32 v153, v157
	v_permlane32_swap_b32_e32 v154, v158
	v_permlane32_swap_b32_e32 v155, v159
	s_nop 0
	global_store_dwordx4 v[208:209], v[152:155], off
	global_store_dwordx4 v[208:209], v[156:159], off offset:64
	v_pk_mul_f32 v[160:161], v[86:87], v[196:197]
	v_pk_mul_f32 v[162:163], v[88:89], v[190:191]
	v_pk_mul_f32 v[164:165], v[82:83], v[192:193]
	v_pk_mul_f32 v[166:167], v[84:85], v[188:189]
	s_nop 1
	v_permlane32_swap_b32_e32 v160, v164
	v_permlane32_swap_b32_e32 v161, v165
	v_permlane32_swap_b32_e32 v162, v166
	v_permlane32_swap_b32_e32 v163, v167
	s_nop 0
	global_store_dwordx4 v[208:209], v[160:163], off offset:512
	global_store_dwordx4 v[208:209], v[164:167], off offset:576
	v_pk_mul_f32 v[168:169], v[78:79], v[202:203]
	v_pk_mul_f32 v[170:171], v[80:81], v[198:199]
	v_pk_mul_f32 v[172:173], v[74:75], v[200:201]
	v_pk_mul_f32 v[174:175], v[76:77], v[194:195]
	s_nop 1
	v_permlane32_swap_b32_e32 v168, v172
	v_permlane32_swap_b32_e32 v169, v173
	v_permlane32_swap_b32_e32 v170, v174
	v_permlane32_swap_b32_e32 v171, v175
	s_nop 0
	global_store_dwordx4 v[210:211], v[168:171], off
	global_store_dwordx4 v[210:211], v[172:175], off offset:64
	v_pk_mul_f32 v[176:177], v[70:71], v[196:197]
	v_pk_mul_f32 v[178:179], v[72:73], v[190:191]
	v_pk_mul_f32 v[180:181], v[66:67], v[192:193]
	v_pk_mul_f32 v[182:183], v[68:69], v[188:189]
	s_nop 1
	v_permlane32_swap_b32_e32 v176, v180
	v_permlane32_swap_b32_e32 v177, v181
	v_permlane32_swap_b32_e32 v178, v182
	v_permlane32_swap_b32_e32 v179, v183
	s_nop 0
	global_store_dwordx4 v[210:211], v[176:179], off offset:512
	global_store_dwordx4 v[210:211], v[180:183], off offset:576
	v_pk_mul_f32 v[152:153], v[62:63], v[202:203]
	v_pk_mul_f32 v[154:155], v[64:65], v[198:199]
	v_pk_mul_f32 v[156:157], v[58:59], v[200:201]
	v_pk_mul_f32 v[158:159], v[60:61], v[194:195]
	s_nop 1
	v_permlane32_swap_b32_e32 v152, v156
	v_permlane32_swap_b32_e32 v153, v157
	v_permlane32_swap_b32_e32 v154, v158
	v_permlane32_swap_b32_e32 v155, v159
	s_nop 0
	global_store_dwordx4 v[212:213], v[152:155], off
	global_store_dwordx4 v[212:213], v[156:159], off offset:64
	v_pk_mul_f32 v[160:161], v[54:55], v[196:197]
	v_pk_mul_f32 v[162:163], v[56:57], v[190:191]
	v_pk_mul_f32 v[164:165], v[50:51], v[192:193]
	v_pk_mul_f32 v[166:167], v[52:53], v[188:189]
	s_nop 1
	v_permlane32_swap_b32_e32 v160, v164
	v_permlane32_swap_b32_e32 v161, v165
	v_permlane32_swap_b32_e32 v162, v166
	v_permlane32_swap_b32_e32 v163, v167
	s_nop 0
	global_store_dwordx4 v[212:213], v[160:163], off offset:512
	global_store_dwordx4 v[212:213], v[164:167], off offset:576
	v_pk_mul_f32 v[168:169], v[46:47], v[202:203]
	v_pk_mul_f32 v[170:171], v[48:49], v[198:199]
	v_pk_mul_f32 v[172:173], v[42:43], v[200:201]
	v_pk_mul_f32 v[174:175], v[44:45], v[194:195]
	s_nop 1
	v_permlane32_swap_b32_e32 v168, v172
	v_permlane32_swap_b32_e32 v169, v173
	v_permlane32_swap_b32_e32 v170, v174
	v_permlane32_swap_b32_e32 v171, v175
	s_nop 0
	global_store_dwordx4 v[214:215], v[168:171], off
	global_store_dwordx4 v[214:215], v[172:175], off offset:64
	v_pk_mul_f32 v[176:177], v[38:39], v[196:197]
	v_pk_mul_f32 v[178:179], v[40:41], v[190:191]
	v_pk_mul_f32 v[180:181], v[34:35], v[192:193]
	v_pk_mul_f32 v[182:183], v[36:37], v[188:189]
	s_nop 1
	v_permlane32_swap_b32_e32 v176, v180
	v_permlane32_swap_b32_e32 v177, v181
	v_permlane32_swap_b32_e32 v178, v182
	v_permlane32_swap_b32_e32 v179, v183
	s_nop 0
	global_store_dwordx4 v[214:215], v[176:179], off offset:512
	global_store_dwordx4 v[214:215], v[180:183], off offset:576
	v_pk_mul_f32 v[152:153], v[28:29], v[202:203]
	v_pk_mul_f32 v[154:155], v[30:31], v[198:199]
	v_pk_mul_f32 v[156:157], v[24:25], v[200:201]
	v_pk_mul_f32 v[158:159], v[26:27], v[194:195]
	s_nop 1
	v_permlane32_swap_b32_e32 v152, v156
	v_permlane32_swap_b32_e32 v153, v157
	v_permlane32_swap_b32_e32 v154, v158
	v_permlane32_swap_b32_e32 v155, v159
	s_nop 0
	global_store_dwordx4 v[216:217], v[152:155], off
	global_store_dwordx4 v[216:217], v[156:159], off offset:64
	v_pk_mul_f32 v[160:161], v[20:21], v[196:197]
	v_pk_mul_f32 v[162:163], v[22:23], v[190:191]
	v_pk_mul_f32 v[164:165], v[16:17], v[192:193]
	v_pk_mul_f32 v[166:167], v[18:19], v[188:189]
	s_nop 1
	v_permlane32_swap_b32_e32 v160, v164
	v_permlane32_swap_b32_e32 v161, v165
	v_permlane32_swap_b32_e32 v162, v166
	v_permlane32_swap_b32_e32 v163, v167
	s_nop 0
	global_store_dwordx4 v[216:217], v[160:163], off offset:512
	global_store_dwordx4 v[216:217], v[164:167], off offset:576
	v_pk_mul_f32 v[168:169], v[12:13], v[202:203]
	v_pk_mul_f32 v[170:171], v[14:15], v[198:199]
	v_pk_mul_f32 v[172:173], v[8:9], v[200:201]
	v_pk_mul_f32 v[174:175], v[10:11], v[194:195]
	s_nop 1
	v_permlane32_swap_b32_e32 v168, v172
	v_permlane32_swap_b32_e32 v169, v173
	v_permlane32_swap_b32_e32 v170, v174
	v_permlane32_swap_b32_e32 v171, v175
	s_nop 0
	global_store_dwordx4 v[218:219], v[168:171], off
	global_store_dwordx4 v[218:219], v[172:175], off offset:64
	v_pk_mul_f32 v[176:177], v[4:5], v[196:197]
	v_pk_mul_f32 v[178:179], v[6:7], v[190:191]
	v_pk_mul_f32 v[180:181], v[0:1], v[192:193]
	v_pk_mul_f32 v[182:183], v[2:3], v[188:189]
	s_nop 1
	v_permlane32_swap_b32_e32 v176, v180
	v_permlane32_swap_b32_e32 v177, v181
	v_permlane32_swap_b32_e32 v178, v182
	v_permlane32_swap_b32_e32 v179, v183
	s_nop 0
	global_store_dwordx4 v[218:219], v[176:179], off offset:512
	global_store_dwordx4 v[218:219], v[180:183], off offset:576
	s_cbranch_execnz .LBB0_1352
	s_branch .LBB0_1351
